# P2 items: store-drain wait moved from item end to just before the next item's first loads (overlaps dequeue and prologue setup); prologue second key tile uses the branch-free prefetch path
# speedup vs baseline: 1.0079x; 1.0038x over previous
; __device__ __forceinline__ void phase_p2(const Params& p, int l) {
;     ...
;   while (true) {
;     if (threadIdx.x == 0) *s_item = atomicAdd(p.ctr + l, 1);
;     __syncthreads();
;     const int item = *s_item;
;     __syncthreads();
;     if (item >= Q_CVP) break;
.LBB0_349:
	s_and_saveexec_b64 s[0:1], s[70:71]
	s_cbranch_execz .LBB0_353
	s_cmp_lg_u32 s98, 0
	s_cbranch_scc0 .Ldq_fresh
	v_mov_b32_e32 v0, v245
	v_readlane_b32 s2, v247, 35
	s_nop 1
	v_mov_b32_e32 v1, s2
	ds_write_b32 v1, v0
	s_branch .LBB0_353

; __device__ __forceinline__ void item_conv(const Params& p, int l, int item) {
;   const float* cw = p.conv_w + l * 3 * 512;
;   for (int e = threadIdx.x; e < 128 * 64; e += NTHR) {
;     int tok = item * 128 + (e >> 6), c = (e & 63) * 8;
;     int t, b; bool samp = tok >= NP;
;     if (!samp) { t = tok & 2047; b = tok >> 11; } else { int ts = tok - NP; t = ts & 15; b = ts >> 4; }
;     float y[8];
; #pragma unroll
;     for (int i = 0; i < 8; ++i) y[i] = 0.f;
; #pragma unroll
;     for (int j = 0; j < 3; ++j) {
;       int pi = t + j;
;       float f[8];
;       if (pi >= 2) {
;         uint4 raw = *reinterpret_cast<const uint4*>(p.u + (long)(tok - 2 + j) * 512 + c);
;         unsigned w[4] = {raw.x, raw.y, raw.z, raw.w};
; #pragma unroll
;         for (int i = 0; i < 4; ++i) { f[2 * i] = __uint_as_float(w[i] << 16); f[2 * i + 1] = __uint_as_float(w[i] & 0xffff0000u); }
;       } else if (samp) {
;         const float* ps = p.cconv + ((long)(l * 16 + b) * 2 + pi) * 512 + c;
; #pragma unroll
;         for (int i = 0; i < 8; ++i) f[i] = ps[i];
;       } else {
; #pragma unroll
;         for (int i = 0; i < 8; ++i) f[i] = 0.f;
;       }
; #pragma unroll
;       for (int i = 0; i < 8; ++i) y[i] += f[i] * cw[j * 512 + c + i];
.LBB0_487:
	s_waitcnt vmcnt(0)
	v_readlane_b32 s28, v246, 25
	v_readlane_b32 s29, v246, 26
	v_readlane_b32 s26, v246, 16
	v_readlane_b32 s4, v248, 59
	v_readlane_b32 s5, v248, 60
	v_readlane_b32 s6, v248, 63
	v_readlane_b32 s7, v247, 0
	v_readlane_b32 s8, v248, 24
	v_readlane_b32 s9, v248, 25
	v_and_b32_e32 v249, 63, v188
	v_lshlrev_b32_e32 v251, 5, v249
	v_lshlrev_b32_e32 v249, 4, v249
	v_lshlrev_b32_e32 v250, 4, v188
	v_readfirstlane_b32 s10, v210
	s_add_u32 s12, s28, 0x1000
	s_addc_u32 s13, s29, 0
	global_load_dwordx4 v[0:3], v251, s[28:29]
	global_load_dwordx4 v[4:7], v251, s[28:29] offset:16
	global_load_dwordx4 v[8:11], v251, s[28:29] offset:2048
	global_load_dwordx4 v[12:15], v251, s[28:29] offset:2064
	global_load_dwordx4 v[16:19], v251, s[12:13]
	global_load_dwordx4 v[20:23], v251, s[12:13] offset:16
	s_lshl_b32 s11, s46, 7
	s_add_i32 s10, s10, s11
	s_mov_b32 s11, 0
	s_cmp_gt_u32 s10, 0xffff
	s_cselect_b32 s13, 1, 0
	s_waitcnt vmcnt(0)
	ds_write_b128 v250, v[0:3]
	ds_write_b128 v250, v[4:7] offset:8192
	ds_write_b128 v250, v[8:11] offset:16384
	ds_write_b128 v250, v[12:15] offset:24576
	ds_write_b128 v250, v[16:19] offset:32768
	ds_write_b128 v250, v[20:23] offset:40960
	s_waitcnt lgkmcnt(0)

; __device__ __forceinline__ int otid() { int t = threadIdx.x; asm volatile("" : "+v"(t)); return t; }
; __device__ __forceinline__ void item_attn(const Params& p, int l, int aidx) {
;   const int tid = otid(), wid = __builtin_amdgcn_readfirstlane(tid >> 6), lane = tid & 63, fr = lane & 15, fq = lane >> 4;
;   const bool samp = aidx >= 2048;
;   int b, hd, nq, qpos0, ntiles; long tokq0;
;   const float *kbase, *vbase, *kcache = nullptr, *vcache = nullptr;
;   if (!samp) {
;     int qb = 7 - (aidx >> 8); int r = aidx & 255; b = r >> 3; hd = r & 7;
;     nq = 256; qpos0 = qb * 256; tokq0 = (long)b * 2048 + qpos0; ntiles = qb * 4 + 4;
;     kbase = p.out + OFF_KP + ((long)l * 65536 + (long)b * 2048) * 512 + hd * 64;
;     vbase = p.out + OFF_VP + ((long)l * 65536 + (long)b * 2048) * 512 + hd * 64;
;   } else {
;     int r = aidx - 2048; b = r >> 3; hd = r & 7;
;     nq = 16; qpos0 = 1024; tokq0 = NP + (long)b * 16; ntiles = 17;
;     kbase = p.out + OFF_KS + ((long)l * 256 + (long)b * 16) * 512 + hd * 64;
;     vbase = p.out + OFF_VS + ((long)l * 256 + (long)b * 16) * 512 + hd * 64;
;     kcache = p.ck + ((long)(l * 16 + b) * 1024) * 512 + hd * 64;
;     vcache = p.cv + ((long)(l * 16 + b) * 1024) * 512 + hd * 64;
;   }
;   u16* Ks = reinterpret_cast<u16*>(smem + AKS);
;   u16* VT = reinterpret_cast<u16*>(smem + AVT);
;   bf16x8 qf[2][2];
;   bool rowv[2];
; #pragma unroll
;   for (int n = 0; n < 2; ++n) {
;     int row = 32 * wid + 16 * n + fr;
;     rowv[n] = row < nq;
; #pragma unroll
;     for (int ks = 0; ks < 2; ++ks) {
;       bf16x8 z = {0, 0, 0, 0, 0, 0, 0, 0};
;       if (rowv[n]) z = *reinterpret_cast<const bf16x8*>(p.sq + (tokq0 + row) * 512 + hd * 64 + ks * 32 + fq * 8);
;       qf[n][ks] = z;
;     }
;   }
.LBB0_509:
	v_xor_b32_e32 v241, 16, v215
	v_xor_b32_e32 v242, 32, v215
	v_xor_b32_e32 v243, 48, v215
	v_lshlrev_b32_e32 v241, 2, v241
	v_lshlrev_b32_e32 v242, 2, v242
	v_lshlrev_b32_e32 v243, 2, v243
	s_ashr_i32 s2, s2, 6
	v_and_b32_e32 v33, 15, v32
	s_lshl_b32 s21, s2, 5
	v_readlane_b32 s48, v247, 7
	v_or_b32_e32 v84, s21, v33
	s_lshl_b64 s[44:45], s[28:29], 1
	v_readlane_b32 s52, v247, 11
	v_readlane_b32 s53, v247, 12
	s_add_u32 s0, s52, s44
	v_ashrrev_i32_e32 v85, 31, v84
	s_addc_u32 s1, s53, s45
	v_and_b32_e32 v190, 48, v32
	v_lshl_add_u64 v[0:1], s[34:35], 0, v[84:85]
	v_lshl_add_u64 v[8:9], s[0:1], 0, v[190:191]
	v_lshlrev_b64 v[82:83], 10, v[0:1]
	v_cmp_gt_i32_e64 s[8:9], s47, v84
	v_lshl_add_u64 v[10:11], v[8:9], 0, v[82:83]
	v_mov_b32_e32 v0, 0
	v_mov_b32_e32 v4, 0
	v_mov_b32_e32 v5, 0
	v_mov_b32_e32 v6, 0
	v_mov_b32_e32 v7, 0
	v_readlane_b32 s49, v247, 8
	v_readlane_b32 s50, v247, 9
	v_readlane_b32 s51, v247, 10
	v_readlane_b32 s54, v247, 13
	v_readlane_b32 s55, v247, 14
	v_readlane_b32 s56, v247, 15
	v_readlane_b32 s57, v247, 16
	v_readlane_b32 s58, v247, 17
	v_readlane_b32 s59, v247, 18
	v_readlane_b32 s60, v247, 19
	v_readlane_b32 s61, v247, 20
	v_readlane_b32 s62, v247, 21
	v_readlane_b32 s63, v247, 22
	s_waitcnt vmcnt(0)
	s_and_saveexec_b64 s[0:1], s[8:9]
	s_cbranch_execz .LBB0_511
	global_load_dwordx4 v[4:7], v[10:11], off

; __device__ __forceinline__ void item_attn(const Params& p, int l, int aidx) {
;     ...
;   ATT_LOAD_TILE(ntiles - 1, 0);
;   if (ntiles > 1) ATT_LOAD_TILE(ntiles - 2, 1);
.LBB0_524:
	v_lshlrev_b32_e32 v18, 2, v32
	v_and_b32_e32 v34, 60, v18
	v_lshlrev_b32_e32 v190, 2, v34
	v_lshl_add_u64 v[16:17], v[16:17], 0, v[190:191]
	global_load_dwordx4 v[16:19], v[16:17], off
	v_add_u32_e32 v20, 0x200, v32
	v_ashrrev_i32_e32 v89, 4, v20
	v_lshl_add_u32 v229, v87, 11, v190
	v_lshl_add_u32 v230, v89, 11, v190
	s_and_b64 vcc, exec, s[12:13]
	v_add_u32_e32 v20, s3, v89
	s_cbranch_vccnz .LBB0_530
	v_min_i32_e32 v22, 0x40f, v20
	v_cmp_lt_i32_e32 vcc, s90, v20
	v_ashrrev_i32_e32 v23, 31, v22
	s_and_saveexec_b64 s[0:1], vcc
	s_xor_b64 s[0:1], exec, s[0:1]
	v_lshlrev_b64 v[20:21], 11, v[22:23]
	s_mov_b32 s4, 0xffe00000
	v_lshl_add_u64 v[20:21], s[36:37], 0, v[20:21]
	s_mov_b32 s5, -1
	v_lshl_add_u64 v[20:21], v[20:21], 0, s[4:5]
	s_andn2_saveexec_b64 s[0:1], s[0:1]
	v_lshlrev_b64 v[20:21], 11, v[22:23]
	v_lshl_add_u64 v[20:21], s[40:41], 0, v[20:21]
	s_or_b64 exec, exec, s[0:1]
	s_branch .LBB0_531

; __device__ __forceinline__ void item_attn(const Params& p, int l, int aidx) {
;     ...
;   ATT_LOAD_TILE(ntiles - 1, 0);
;   if (ntiles > 1) ATT_LOAD_TILE(ntiles - 2, 1);
.Lkvfast_p2:
	s_mov_b32 s2, s49
	s_ashr_i32 s3, s2, 31
	s_lshl_b64 s[100:101], s[2:3], 11
	s_add_u32 s100, s36, s100
	s_addc_u32 s101, s37, s101
	global_load_dwordx4 v[24:27], v229, s[100:101]
	global_load_dwordx4 v[28:31], v230, s[100:101]
	s_add_i32 s0, s48, s19
	s_addk_i32 s0, 0xff80
	s_ashr_i32 s1, s0, 31
	s_lshl_b64 s[2:3], s[0:1], 11
	s_add_u32 s4, s38, s2
	s_addc_u32 s5, s39, s3
	global_load_dword v109, v102, s[4:5]
	global_load_dword v111, v102, s[4:5] offset:2048
	s_add_u32 s4, s4, 0x1000
	s_addc_u32 s5, s5, 0
	global_load_dword v112, v102, s[4:5]
	global_load_dword v122, v102, s[4:5] offset:2048
	s_add_u32 s4, s4, 0x1000
	s_addc_u32 s5, s5, 0
	global_load_dword v123, v102, s[4:5]
	global_load_dword v124, v102, s[4:5] offset:2048
	s_add_u32 s4, s4, 0x1000
	s_addc_u32 s5, s5, 0
	global_load_dword v125, v102, s[4:5]
	global_load_dword v126, v102, s[4:5] offset:2048
	s_branch .Lkvp2_done

; __device__ __forceinline__ void item_attn(const Params& p, int l, int aidx) {
;     ...
;   const bool wave_has_rows = (32 * wid) < nq;
;   f32x4 oacc[4][2];
; #pragma unroll
;   for (int md = 0; md < 4; ++md)
; #pragma unroll
;     for (int n = 0; n < 2; ++n) oacc[md][n] = f32x4{0.f, 0.f, 0.f, 0.f};
;   float carry[2] = {1.f, 1.f};
;   const int wave_qmax = qpos0 + 32 * wid + 31;
;   float4 kreg[2][2]; float vreg[2][8];
.Lkvp2_done:
	s_cmp_ge_i32 s21, s47
	s_cselect_b64 s[0:1], -1, 0
	s_lshl_b32 s2, s48, 1
	s_addk_i32 s2, 0x100
	v_bfe_u32 v32, v32, 4, 2
	v_mov_b32_e32 v38, s2
	s_movk_i32 s2, 0x90
	v_mad_u32_u24 v115, v35, s2, v38
	v_xor_b32_e32 v35, 1, v32
	v_cmp_gt_u32_e64 s[14:15], v35, v32
	v_xor_b32_e32 v35, 2, v32
	v_lshlrev_b32_e32 v36, 3, v32
	v_or_b32_e32 v37, s20, v33
	v_cmp_gt_u32_e64 s[16:17], v35, v32
	v_xor_b32_e32 v35, 3, v32
	s_add_i32 s52, s18, -1
	v_lshl_add_u32 v34, v34, 1, v216
	v_lshlrev_b32_e32 v114, 2, v32
	v_cmp_gt_u32_e64 s[18:19], v35, v32
	v_add_u32_e32 v85, s21, v37
	v_mul_lo_u32 v32, v87, s2
	v_mul_lo_u32 v35, v89, s2
	v_mul_u32_u24_e32 v33, 0x90, v33
	v_lshlrev_b32_e32 v37, 1, v36
	s_movk_i32 s2, 0x100
	v_mov_b32_e32 v60, v191
	v_mov_b32_e32 v61, v191
	s_add_i32 s50, s20, s21
	v_add3_u32 v118, s2, v33, v37
	v_sub_u32_e32 v119, 0, v36
	v_mov_b32_e32 v199, v198
	v_mov_b32_e32 v62, v191
	v_mov_b32_e32 v63, v191
	v_add_u32_e32 v120, v34, v32
	v_add_u32_e32 v121, v34, v35
	v_mov_b64_e32 v[44:45], v[60:61]
	v_mov_b64_e32 v[56:57], v[60:61]
	v_mov_b64_e32 v[36:37], v[60:61]
	v_mov_b64_e32 v[52:53], v[60:61]
	v_mov_b64_e32 v[40:41], v[60:61]
	v_mov_b64_e32 v[48:49], v[60:61]
	v_mov_b64_e32 v[32:33], v[60:61]
	s_or_b32 s51, s50, 31
	v_add_u32_e32 v88, s20, v86
	v_sub_u32_e32 v116, 0x40f, v87
	v_sub_u32_e32 v117, 0x40f, v89
	v_mov_b64_e32 v[46:47], v[62:63]
	v_mov_b64_e32 v[58:59], v[62:63]
	v_mov_b64_e32 v[38:39], v[62:63]
	v_mov_b64_e32 v[54:55], v[62:63]
	v_mov_b64_e32 v[42:43], v[62:63]
	v_mov_b64_e32 v[50:51], v[62:63]
	v_mov_b64_e32 v[34:35], v[62:63]
	v_mov_b64_e32 v[90:91], v[198:199]
	s_branch .LBB0_629

; __device__ __forceinline__ int otid() { int t = threadIdx.x; asm volatile("" : "+v"(t)); return t; }
; __device__ __forceinline__ void item_hgrn(const Params& p, int l, int sidx) {
;   const int tid = otid(), wid = __builtin_amdgcn_readfirstlane(tid >> 6), lane = tid & 63, fr = lane & 15, fq = lane >> 4;
;   const bool samp = sidx >= 128;
;   int b, hh, T, tok0, nchunks;
;   if (!samp) { b = sidx >> 2; hh = sidx & 3; T = 2048; tok0 = b * 2048; nchunks = 32; }
;   else { int s = sidx - 128; b = s >> 2; hh = s & 3; T = 16; tok0 = NP + b * 16; nchunks = 1; }
.LBB0_791:
	s_waitcnt vmcnt(0)
	v_mov_b32_e32 v94, v188
	s_cmpk_lt_i32 s46, 0x80
	s_cselect_b64 s[0:1], -1, 0
	v_readfirstlane_b32 s2, v94
	s_cmpk_gt_i32 s46, 0x7f
	s_mov_b64 s[4:5], -1
	s_cbranch_scc1 .LBB0_793
	s_ashr_i32 s90, s46, 2
	s_lshl_b32 s91, s90, 11
	s_mov_b64 s[4:5], 0
